# v37 + first ticket of each attention phase popped at the top of the phase-entry code
# speedup vs baseline: 1.0077x; 1.0014x over previous
.LBB0_151:
	v_readlane_b32 s0, v252, 0
	s_mov_b32 s78, s0
	v_readlane_b32 s0, v254, 5
	s_ashr_i32 s2, s0, 2
	s_and_b32 s3, s0, 3
	s_lshl_b32 s0, s2, 6
	s_ashr_i32 s1, s0, 31
	v_writelane_b32 v254, s0, 8
	s_lshl_b32 s79, s2, 5
	s_lshl_b32 s4, s2, 9
	v_writelane_b32 v254, s1, 9
	s_mov_b32 s0, s2
	v_writelane_b32 v254, s0, 10
	s_mov_b64 s[10:11], -1
	s_mov_b64 s[12:13], 0
	v_writelane_b32 v254, s1, 11
	s_lshl_b32 s0, s2, 4
	v_writelane_b32 v254, s0, 12
	v_writelane_b32 v254, s73, 13
	v_writelane_b32 v254, s80, 14
	s_cmp_lt_i32 s3, 2
	s_mov_b64 s[8:9], 0
	v_writelane_b32 v254, s81, 15
	s_cbranch_scc1 .LBB0_359
	s_cmp_eq_u32 s3, 2
	s_mov_b64 s[8:9], -1
	s_cbranch_scc0 .LBB0_358
	v_writelane_b32 v254, s3, 16
	v_cmp_eq_u32_e64 s[42:43], 0, v218
	v_readlane_b32 s0, v254, 8
	v_readlane_b32 s1, v254, 9
	s_lshl_b64 s[2:3], s[0:1], 2
	v_readlane_b32 s0, v252, 13
	s_add_u32 s2, s0, s2
	v_readlane_b32 s0, v252, 14
	s_addc_u32 s3, s0, s3
	v_writelane_b32 v254, s2, 17
	s_nop 1
	v_writelane_b32 v254, s3, 18
	s_nop 0
	v_mov_b32_e32 v182, s2
	v_mov_b32_e32 v183, s3
	s_mov_b64 s[100:101], exec
	s_mov_b64 exec, s[42:43]
	global_atomic_add v221, v[182:183], v181, off sc0
	s_mov_b64 exec, s[100:101]
	v_readlane_b32 s0, v254, 10
	v_readlane_b32 s1, v254, 11
	s_lshl_b32 s0, s0, 3
	s_ashr_i32 s1, s0, 31
	v_writelane_b32 v254, s0, 19
	s_nop 1
	v_writelane_b32 v254, s1, 20
	s_add_u32 s0, s88, 0x4800000
	v_writelane_b32 v254, s0, 21
	s_addc_u32 s0, s89, 0
	v_writelane_b32 v254, s0, 23
	s_add_u32 s0, s88, 0x4e00000
	v_writelane_b32 v254, s0, 24
	s_addc_u32 s0, s89, 0
	v_writelane_b32 v254, s0, 25
	s_add_u32 s0, s88, 0x5000000
	v_writelane_b32 v254, s0, 26
	s_addc_u32 s0, s89, 0
	v_writelane_b32 v254, s0, 27
	s_add_u32 s0, s88, 0x6900000
	v_writelane_b32 v254, s0, 28
	s_addc_u32 s0, s89, 0
	v_writelane_b32 v254, s0, 30
	s_add_u32 s0, s88, 0x8200000
	v_writelane_b32 v254, s0, 31
	s_addc_u32 s0, s89, 0
	v_writelane_b32 v254, s0, 33
	s_add_u32 s0, s88, 0x8e00000
	v_writelane_b32 v254, s0, 34
	s_addc_u32 s0, s89, 0
	v_writelane_b32 v254, s0, 36
	s_add_u32 s0, s88, 0x5800000
	v_writelane_b32 v254, s0, 37
	s_addc_u32 s0, s89, 0
	v_writelane_b32 v254, s0, 39
	s_add_u32 s0, s88, 0xa00000
	v_writelane_b32 v254, s0, 41
	s_addc_u32 s0, s89, 0
	v_writelane_b32 v254, s0, 43
	s_add_u32 s0, s88, 0x400000
	v_writelane_b32 v254, s0, 44
	s_addc_u32 s0, s89, 0
	v_writelane_b32 v254, s0, 46
	s_add_u32 s0, s88, 0x600000
	v_writelane_b32 v254, s0, 48
	s_addc_u32 s0, s89, 0
	v_writelane_b32 v254, s0, 50
	s_add_u32 s0, s88, 0x3c00000
	v_writelane_b32 v254, s0, 52
	s_addc_u32 s0, s89, 0
	v_writelane_b32 v254, s0, 53
	s_add_u32 s0, s88, 0x4000000
	v_writelane_b32 v254, s0, 54
	s_addc_u32 s0, s89, 0
	v_writelane_b32 v254, s0, 56
	s_add_u32 s0, s88, 0x4400000
	v_writelane_b32 v254, s0, 57
	s_addc_u32 s0, s89, 0
	s_cmp_eq_u32 s73, 0
	v_writelane_b32 v254, s0, 58
	s_cselect_b64 s[12:13], -1, 0
	s_add_u32 s0, s88, 0x8000
	v_writelane_b32 v254, s0, 59
	s_addc_u32 s0, s89, 0
	s_add_u32 s14, s88, 0x4200
	v_writelane_b32 v254, s0, 60
	s_addc_u32 s15, s89, 0
	s_and_b32 s0, s73, 3
	s_ashr_i32 s2, s73, 2
	s_lshl_b32 s1, s2, 5
	s_lshl_b32 s2, s2, 12
	s_lshl_b32 s3, s0, 10
	s_or_b32 s80, s2, s3
	s_lshl_b32 s51, s73, 5
	s_lshl_b32 s5, s0, 12
	s_addk_i32 s80, 0x3000
	s_lshl_b32 s16, s73, 10
	s_lshl_b32 s10, s73, 3
	s_and_b32 s6, s51, 32
	s_add_i32 s7, s5, s1
	s_add_i32 s17, s16, 0
	s_add_i32 s38, s80, 0
	s_bfe_u32 s2, s73, 0x10001
	s_cmp_eq_u32 s2, 0
	s_cselect_b64 s[8:9], -1, 0
	v_writelane_b32 v254, s8, 61
	s_add_u32 s5, s88, 0xa200
	s_mov_b32 s81, s1
	v_writelane_b32 v254, s9, 62
	v_writelane_b32 v254, s5, 63
	s_addc_u32 s5, s89, 0
	s_cmp_lt_i32 s73, 4
	v_writelane_b32 v255, s5, 0
	s_cselect_b64 s[8:9], -1, 0
	v_writelane_b32 v255, s8, 2
	s_lshl_b32 s2, s2, 16
	v_readlane_b32 s5, v252, 15
	v_writelane_b32 v255, s9, 3
	s_add_u32 s2, s5, s2
	v_readlane_b32 s5, v252, 16
	s_addc_u32 s5, s5, 0
	v_writelane_b32 v255, s6, 4
	s_lshl_b32 s6, s6, 8
	s_add_u32 s2, s2, s6
	v_writelane_b32 v255, s2, 6
	s_addc_u32 s2, s5, 0
	v_writelane_b32 v255, s2, 7
	s_add_u32 s2, s88, 0x300000
	v_writelane_b32 v255, s2, 8
	s_addc_u32 s2, s89, 0
	s_add_u32 s39, s88, 0x1800
	s_addc_u32 s8, s89, 0
	v_writelane_b32 v255, s2, 9
	s_add_u32 s2, s88, 0x9000
	v_writelane_b32 v255, s2, 10
	s_addc_u32 s2, s89, 0
	v_writelane_b32 v255, s2, 11
	s_lshl_b32 s2, s73, 9
	s_add_i32 s2, s2, 0
	s_add_i32 s2, s2, 0x21800
	v_writelane_b32 v255, s2, 12
	s_add_u32 s18, s88, 0x5900000
	s_mul_i32 s2, s73, 0x2200
	s_addc_u32 s19, s89, 0
	s_add_i32 s9, s2, 0
	s_add_u32 s26, s88, 0x7200000
	s_addc_u32 s27, s89, 0
	s_lshl_b32 s2, s0, 11
	v_writelane_b32 v255, s7, 13
	s_sub_i32 s5, s7, s2
	v_writelane_b32 v255, s5, 14
	s_lshl_b32 s5, s73, 7
	s_add_i32 s6, s5, 0
	s_add_i32 s6, s6, 0x22800
	s_add_u32 s5, s88, 0x9800
	v_writelane_b32 v255, s5, 15
	s_addc_u32 s5, s89, 0
	v_writelane_b32 v255, s5, 16
	s_add_u32 s5, s88, 0x8800
	v_writelane_b32 v255, s5, 17
	s_addc_u32 s5, s89, 0
	v_writelane_b32 v255, s5, 18
	s_lshl_b32 s5, s0, 4
	s_add_i32 s3, s3, 0
	v_writelane_b32 v255, s5, 19
	s_add_i32 s7, s3, 0x2000
	v_writelane_b32 v255, s3, 20
	s_add_u32 s3, s88, 0x4410000
	v_writelane_b32 v255, s3, 22
	s_addc_u32 s3, s89, 0
	v_writelane_b32 v255, s3, 23
	s_add_u32 s3, s88, 0x4010000
	v_writelane_b32 v255, s3, 24
	s_addc_u32 s3, s89, 0
	v_writelane_b32 v255, s3, 25
	s_lshl_b32 s3, s73, 11
	v_writelane_b32 v255, s3, 26
	s_add_i32 s2, s2, s1
	v_writelane_b32 v255, s2, 27
	s_lshl_b32 s2, s0, 9
	s_mulk_i32 s0, 0x3000
	v_writelane_b32 v255, s2, 29
	s_add_i32 s0, s0, s1
	v_writelane_b32 v255, s0, 30
	v_and_b32_e32 v174, 31, v205
	v_add_u32_e32 v174, s79, v174
	v_lshlrev_b32_e32 v174, 4, v174
	v_lshrrev_b32_e32 v175, 5, v205
	v_lshl_add_u32 v174, v175, 12, v174
	v_mov_b32_e32 v175, 0
	v_readlane_b32 s100, v254, 59
	v_readlane_b32 s101, v254, 60
	s_nop 1
	v_lshl_add_u64 v[174:175], s[100:101], 0, v[174:175]
	v_readlane_b32 s100, v254, 17
	v_readlane_b32 s101, v254, 18
	s_nop 3
	v_mov_b32_e32 v182, s100
	v_mov_b32_e32 v183, s101
	s_mov_b64 s[100:101], exec
	s_mov_b64 exec, s[12:13]
	global_load_dword v184, v[174:175], off sc1
	s_mov_b64 exec, s[100:101]
	s_branch .LBB0_156
